# SSD items: the wave prefix scan of dt*A uses six DPP adds (row shifts + row_bcast fix-ups) instead of six ds_bpermute round trips
# speedup vs baseline: 1.0099x; 1.0041x over previous
; __device__ __forceinline__ float bf2f(bf16_t h) { return __uint_as_float(((unsigned)h) << 16); }
; __device__ __forceinline__ void ssd_item(const Args& a, LAS unsigned char* lds, int layer, bool is_sample, int b, int h, int seq_row0, int nchunks,
;                                          bf16_t* proj, float* ssq, const int tid) {
;     ...
;                 const float x = bf2f(dr[q]) + dtb;
;                 const float dt = x > 20.f ? x : log1pf(__expf(x));
;                 float sc = dt * Aneg;
; #pragma unroll
;                 for (int off = 1; off < 64; off <<= 1) { const float v = __shfl_up(sc, off); if (lane >= off) sc += v; }
;                 dt_all[cc * 64 + lane] = dt; ac_all[cc * 64 + lane] = sc * 1.4426950408889634f; } }
.LBB0_494:
	s_or_b64 exec, exec, s[16:17]
	v_add_u32_e32 v101, -1, v201
	v_cmp_lt_i32_e32 vcc, v101, v202
	v_mul_f32_e64 v100, v99, -v83
	s_and_b32 s16, s44, 0x3fffffc0
	v_cndmask_b32_e32 v101, v101, v201, vcc
	v_lshlrev_b32_e32 v101, 2, v101
	v_cmp_eq_u32_e32 vcc, 0, v95
	s_waitcnt lgkmcnt(0)
	s_nop 1
	v_add_f32_dpp v100, v100, v100 row_shr:1 row_mask:0xf bank_mask:0xf
	v_add_u32_e32 v101, -2, v201
	v_cmp_lt_i32_e32 vcc, v101, v202
	s_nop 1
	v_cndmask_b32_e32 v101, v101, v201, vcc
	v_lshlrev_b32_e32 v101, 2, v101
	v_cmp_gt_u32_e32 vcc, 2, v95
	s_waitcnt lgkmcnt(0)
	s_nop 1
	v_add_f32_dpp v100, v100, v100 row_shr:2 row_mask:0xf bank_mask:0xf
	v_add_u32_e32 v101, -4, v201
	v_cmp_lt_i32_e32 vcc, v101, v202
	s_nop 1
	v_cndmask_b32_e32 v101, v101, v201, vcc
	v_lshlrev_b32_e32 v101, 2, v101
	v_cmp_gt_u32_e32 vcc, 4, v95
	s_waitcnt lgkmcnt(0)
	s_nop 1
	v_add_f32_dpp v100, v100, v100 row_shr:4 row_mask:0xf bank_mask:0xf
	v_add_u32_e32 v101, -8, v201
	v_cmp_lt_i32_e32 vcc, v101, v202
	s_nop 1
	v_cndmask_b32_e32 v101, v101, v201, vcc
	v_lshlrev_b32_e32 v101, 2, v101
	v_cmp_gt_u32_e32 vcc, 8, v95
	s_waitcnt lgkmcnt(0)
	s_nop 1
	v_add_f32_dpp v100, v100, v100 row_shr:8 row_mask:0xf bank_mask:0xf
	v_add_u32_e32 v101, -16, v201
	v_cmp_lt_i32_e32 vcc, v101, v202
	s_nop 1
	v_cndmask_b32_e32 v101, v101, v201, vcc
	v_lshlrev_b32_e32 v101, 2, v101
	v_cmp_gt_u32_e32 vcc, 16, v95
	s_waitcnt lgkmcnt(0)
	s_nop 1
	v_add_f32_dpp v100, v100, v100 row_bcast:15 row_mask:0xa bank_mask:0xf
	v_subrev_u32_e32 v101, 32, v201
	v_cmp_lt_i32_e32 vcc, v101, v202
	s_nop 1
	v_cndmask_b32_e32 v101, v101, v201, vcc
	v_lshlrev_b32_e32 v101, 2, v101
	v_cmp_gt_u32_e32 vcc, 32, v95
	s_waitcnt lgkmcnt(0)
	s_nop 1
	v_add_f32_dpp v100, v100, v100 row_bcast:31 row_mask:0xc bank_mask:0xf
	v_or_b32_e32 v101, s16, v95
	v_lshl_add_u32 v101, v101, 2, 0
	v_add_u32_e32 v102, 0x1a640, v101
	ds_write_b32 v102, v99
	v_mul_f32_e32 v99, 0x3fb8aa3b, v100
	v_add_u32_e32 v100, 0x1c640, v101
	ds_write_b32 v100, v99
	s_andn2_b64 vcc, exec, s[14:15]
	s_cbranch_vccz .LBB0_501

; __device__ __forceinline__ float bf2f(bf16_t h) { return __uint_as_float(((unsigned)h) << 16); }
; __device__ __forceinline__ void ssd_item(const Args& a, LAS unsigned char* lds, int layer, bool is_sample, int b, int h, int seq_row0, int nchunks,
;                                          bf16_t* proj, float* ssq, const int tid) {
;     ...
;                 const float x = bf2f(dr[q]) + dtb;
;                 const float dt = x > 20.f ? x : log1pf(__expf(x));
;                 float sc = dt * Aneg;
; #pragma unroll
;                 for (int off = 1; off < 64; off <<= 1) { const float v = __shfl_up(sc, off); if (lane >= off) sc += v; }
;                 dt_all[cc * 64 + lane] = dt; ac_all[cc * 64 + lane] = sc * 1.4426950408889634f; } }
.LBB0_498:
	s_or_b64 exec, exec, s[8:9]
	v_add_u32_e32 v99, -1, v201
	v_cmp_lt_i32_e32 vcc, v99, v202
	v_mul_f32_e64 v93, v85, -v83
	s_nop 0
	v_cndmask_b32_e32 v99, v99, v201, vcc
	v_lshlrev_b32_e32 v99, 2, v99
	v_cmp_eq_u32_e32 vcc, 0, v95
	s_waitcnt lgkmcnt(0)
	s_nop 1
	v_add_f32_dpp v93, v93, v93 row_shr:1 row_mask:0xf bank_mask:0xf
	v_add_u32_e32 v99, -2, v201
	v_cmp_lt_i32_e32 vcc, v99, v202
	s_nop 1
	v_cndmask_b32_e32 v99, v99, v201, vcc
	v_lshlrev_b32_e32 v99, 2, v99
	v_cmp_gt_u32_e32 vcc, 2, v95
	s_waitcnt lgkmcnt(0)
	s_nop 1
	v_add_f32_dpp v93, v93, v93 row_shr:2 row_mask:0xf bank_mask:0xf
	v_add_u32_e32 v99, -4, v201
	v_cmp_lt_i32_e32 vcc, v99, v202
	s_nop 1
	v_cndmask_b32_e32 v99, v99, v201, vcc
	v_lshlrev_b32_e32 v99, 2, v99
	v_cmp_gt_u32_e32 vcc, 4, v95
	s_waitcnt lgkmcnt(0)
	s_nop 1
	v_add_f32_dpp v93, v93, v93 row_shr:4 row_mask:0xf bank_mask:0xf
	v_add_u32_e32 v99, -8, v201
	v_cmp_lt_i32_e32 vcc, v99, v202
	s_nop 1
	v_cndmask_b32_e32 v99, v99, v201, vcc
	v_lshlrev_b32_e32 v99, 2, v99
	v_cmp_gt_u32_e32 vcc, 8, v95
	s_waitcnt lgkmcnt(0)
	s_nop 1
	v_add_f32_dpp v93, v93, v93 row_shr:8 row_mask:0xf bank_mask:0xf
	v_add_u32_e32 v99, -16, v201
	v_cmp_lt_i32_e32 vcc, v99, v202
	s_nop 1
	v_cndmask_b32_e32 v99, v99, v201, vcc
	v_lshlrev_b32_e32 v99, 2, v99
	v_cmp_gt_u32_e32 vcc, 16, v95
	s_waitcnt lgkmcnt(0)
	s_nop 1
	v_add_f32_dpp v93, v93, v93 row_bcast:15 row_mask:0xa bank_mask:0xf
	v_subrev_u32_e32 v99, 32, v201
	v_cmp_lt_i32_e32 vcc, v99, v202
	s_nop 1
	v_cndmask_b32_e32 v99, v99, v201, vcc
	v_lshlrev_b32_e32 v99, 2, v99
	v_cmp_gt_u32_e32 vcc, 32, v95
	s_waitcnt lgkmcnt(0)
	s_nop 1
	v_add_f32_dpp v93, v93, v93 row_bcast:31 row_mask:0xc bank_mask:0xf
	v_lshlrev_b32_e32 v99, 2, v95
	v_lshl_or_b32 v99, s42, 8, v99
	v_add_u32_e32 v99, 0, v99
	v_add_u32_e32 v100, 0x1a640, v99
	ds_write_b32 v100, v85
	v_mul_f32_e32 v85, 0x3fb8aa3b, v93
	v_add_u32_e32 v93, 0x1c640, v99
	ds_write_b32 v93, v85
	s_andn2_b64 vcc, exec, s[6:7]
	s_cbranch_vccnz .LBB0_508
	s_branch .LBB0_505

; __device__ __forceinline__ float bf2f(bf16_t h) { return __uint_as_float(((unsigned)h) << 16); }
; __device__ __forceinline__ void ssd_item(const Args& a, LAS unsigned char* lds, int layer, bool is_sample, int b, int h, int seq_row0, int nchunks,
;                                          bf16_t* proj, float* ssq, const int tid) {
;     ...
;                 const float x = bf2f(dr[q]) + dtb;
;                 const float dt = x > 20.f ? x : log1pf(__expf(x));
;                 float sc = dt * Aneg;
; #pragma unroll
;                 for (int off = 1; off < 64; off <<= 1) { const float v = __shfl_up(sc, off); if (lane >= off) sc += v; }
;                 dt_all[cc * 64 + lane] = dt; ac_all[cc * 64 + lane] = sc * 1.4426950408889634f; } }
.LBB0_503:
	s_or_b64 exec, exec, s[14:15]
	v_add_u32_e32 v100, -1, v201
	v_cmp_lt_i32_e32 vcc, v100, v202
	v_mul_f32_e64 v99, v93, -v83
	s_nop 0
	v_cndmask_b32_e32 v100, v100, v201, vcc
	v_lshlrev_b32_e32 v100, 2, v100
	v_cmp_eq_u32_e32 vcc, 0, v95
	s_waitcnt lgkmcnt(0)
	s_nop 1
	v_add_f32_dpp v99, v99, v99 row_shr:1 row_mask:0xf bank_mask:0xf
	v_add_u32_e32 v100, -2, v201
	v_cmp_lt_i32_e32 vcc, v100, v202
	s_nop 1
	v_cndmask_b32_e32 v100, v100, v201, vcc
	v_lshlrev_b32_e32 v100, 2, v100
	v_cmp_gt_u32_e32 vcc, 2, v95
	s_waitcnt lgkmcnt(0)
	s_nop 1
	v_add_f32_dpp v99, v99, v99 row_shr:2 row_mask:0xf bank_mask:0xf
	v_add_u32_e32 v100, -4, v201
	v_cmp_lt_i32_e32 vcc, v100, v202
	s_nop 1
	v_cndmask_b32_e32 v100, v100, v201, vcc
	v_lshlrev_b32_e32 v100, 2, v100
	v_cmp_gt_u32_e32 vcc, 4, v95
	s_waitcnt lgkmcnt(0)
	s_nop 1
	v_add_f32_dpp v99, v99, v99 row_shr:4 row_mask:0xf bank_mask:0xf
	v_add_u32_e32 v100, -8, v201
	v_cmp_lt_i32_e32 vcc, v100, v202
	s_nop 1
	v_cndmask_b32_e32 v100, v100, v201, vcc
	v_lshlrev_b32_e32 v100, 2, v100
	v_cmp_gt_u32_e32 vcc, 8, v95
	s_waitcnt lgkmcnt(0)
	s_nop 1
	v_add_f32_dpp v99, v99, v99 row_shr:8 row_mask:0xf bank_mask:0xf
	v_add_u32_e32 v100, -16, v201
	v_cmp_lt_i32_e32 vcc, v100, v202
	s_nop 1
	v_cndmask_b32_e32 v100, v100, v201, vcc
	v_lshlrev_b32_e32 v100, 2, v100
	v_cmp_gt_u32_e32 vcc, 16, v95
	s_waitcnt lgkmcnt(0)
	s_nop 1
	v_add_f32_dpp v99, v99, v99 row_bcast:15 row_mask:0xa bank_mask:0xf
	v_subrev_u32_e32 v100, 32, v201
	v_cmp_lt_i32_e32 vcc, v100, v202
	s_nop 1
	v_cndmask_b32_e32 v100, v100, v201, vcc
	v_lshlrev_b32_e32 v100, 2, v100
	v_cmp_gt_u32_e32 vcc, 32, v95
	s_waitcnt lgkmcnt(0)
	s_nop 1
	v_add_f32_dpp v99, v99, v99 row_bcast:31 row_mask:0xc bank_mask:0xf
	v_lshlrev_b32_e32 v100, 2, v95
	v_lshl_or_b32 v100, s43, 8, v100
	v_add_u32_e32 v100, 0, v100
	v_add_u32_e32 v101, 0x1a640, v100
	ds_write_b32 v101, v93
	v_mul_f32_e32 v93, 0x3fb8aa3b, v99
	v_add_u32_e32 v99, 0x1c640, v100
	ds_write_b32 v99, v93
	s_andn2_b64 vcc, exec, s[8:9]
	s_cbranch_vccz .LBB0_496

; __device__ __forceinline__ float bf2f(bf16_t h) { return __uint_as_float(((unsigned)h) << 16); }
; __device__ __forceinline__ void ssd_item(const Args& a, LAS unsigned char* lds, int layer, bool is_sample, int b, int h, int seq_row0, int nchunks,
;                                          bf16_t* proj, float* ssq, const int tid) {
;     ...
;                 const float x = bf2f(dr[q]) + dtb;
;                 const float dt = x > 20.f ? x : log1pf(__expf(x));
;                 float sc = dt * Aneg;
; #pragma unroll
;                 for (int off = 1; off < 64; off <<= 1) { const float v = __shfl_up(sc, off); if (lane >= off) sc += v; }
;                 dt_all[cc * 64 + lane] = dt; ac_all[cc * 64 + lane] = sc * 1.4426950408889634f; } }
.LBB0_507:
	s_or_b64 exec, exec, s[6:7]
	v_add_u32_e32 v85, -1, v201
	v_cmp_lt_i32_e32 vcc, v85, v202
	v_mul_f32_e64 v84, v82, -v83
	s_nop 0
	v_cndmask_b32_e32 v85, v85, v201, vcc
	v_lshlrev_b32_e32 v85, 2, v85
	v_cmp_eq_u32_e32 vcc, 0, v95
	s_waitcnt lgkmcnt(0)
	v_mov_b32_e32 v83, v84
	s_nop 1
	v_add_f32_dpp v83, v83, v83 row_shr:1 row_mask:0xf bank_mask:0xf
	v_add_u32_e32 v84, -2, v201
	v_cmp_lt_i32_e32 vcc, v84, v202
	s_nop 1
	v_cndmask_b32_e32 v84, v84, v201, vcc
	v_lshlrev_b32_e32 v84, 2, v84
	v_cmp_gt_u32_e32 vcc, 2, v95
	s_waitcnt lgkmcnt(0)
	s_nop 1
	v_add_f32_dpp v83, v83, v83 row_shr:2 row_mask:0xf bank_mask:0xf
	v_add_u32_e32 v84, -4, v201
	v_cmp_lt_i32_e32 vcc, v84, v202
	s_nop 1
	v_cndmask_b32_e32 v84, v84, v201, vcc
	v_lshlrev_b32_e32 v84, 2, v84
	v_cmp_gt_u32_e32 vcc, 4, v95
	s_waitcnt lgkmcnt(0)
	s_nop 1
	v_add_f32_dpp v83, v83, v83 row_shr:4 row_mask:0xf bank_mask:0xf
	v_add_u32_e32 v84, -8, v201
	v_cmp_lt_i32_e32 vcc, v84, v202
	s_nop 1
	v_cndmask_b32_e32 v84, v84, v201, vcc
	v_lshlrev_b32_e32 v84, 2, v84
	v_cmp_gt_u32_e32 vcc, 8, v95
	s_waitcnt lgkmcnt(0)
	s_nop 1
	v_add_f32_dpp v83, v83, v83 row_shr:8 row_mask:0xf bank_mask:0xf
	v_add_u32_e32 v84, -16, v201
	v_cmp_lt_i32_e32 vcc, v84, v202
	s_nop 1
	v_cndmask_b32_e32 v84, v84, v201, vcc
	v_lshlrev_b32_e32 v84, 2, v84
	v_cmp_gt_u32_e32 vcc, 16, v95
	s_waitcnt lgkmcnt(0)
	s_nop 1
	v_add_f32_dpp v83, v83, v83 row_bcast:15 row_mask:0xa bank_mask:0xf
	v_subrev_u32_e32 v84, 32, v201
	v_cmp_lt_i32_e32 vcc, v84, v202
	s_nop 1
	v_cndmask_b32_e32 v84, v84, v201, vcc
	v_lshlrev_b32_e32 v84, 2, v84
	v_cmp_gt_u32_e32 vcc, 32, v95
	s_waitcnt lgkmcnt(0)
	s_nop 1
	v_add_f32_dpp v83, v83, v83 row_bcast:31 row_mask:0xc bank_mask:0xf
	v_lshlrev_b32_e32 v84, 2, v95
	v_lshl_or_b32 v84, s41, 8, v84
	v_add_u32_e32 v84, 0, v84
	v_add_u32_e32 v85, 0x1a640, v84
	ds_write_b32 v85, v82
	v_mul_f32_e32 v82, 0x3fb8aa3b, v83
	v_add_u32_e32 v83, 0x1c640, v84
	ds_write_b32 v83, v82

; __device__ __forceinline__ float bf2f(bf16_t h) { return __uint_as_float(((unsigned)h) << 16); }
; __device__ __forceinline__ void ssd_item(const Args& a, LAS unsigned char* lds, int layer, bool is_sample, int b, int h, int seq_row0, int nchunks,
;                                          bf16_t* proj, float* ssq, const int tid) {
;     ...
;                 const float x = bf2f(dr[q]) + dtb;
;                 const float dt = x > 20.f ? x : log1pf(__expf(x));
;                 float sc = dt * Aneg;
; #pragma unroll
;                 for (int off = 1; off < 64; off <<= 1) { const float v = __shfl_up(sc, off); if (lane >= off) sc += v; }
;                 dt_all[cc * 64 + lane] = dt; ac_all[cc * 64 + lane] = sc * 1.4426950408889634f; } }
.LBB0_546:
	s_or_b64 exec, exec, s[16:17]
	v_add_u32_e32 v77, -1, v201
	v_cmp_lt_i32_e32 vcc, v77, v202
	v_mul_f32_e64 v76, v75, -v72
	s_nop 0
	v_cndmask_b32_e32 v77, v77, v201, vcc
	v_lshlrev_b32_e32 v77, 2, v77
	v_cmp_eq_u32_e32 vcc, 0, v68
	s_waitcnt lgkmcnt(0)
	s_nop 1
	v_add_f32_dpp v76, v76, v76 row_shr:1 row_mask:0xf bank_mask:0xf
	v_add_u32_e32 v77, -2, v201
	v_cmp_lt_i32_e32 vcc, v77, v202
	s_nop 1
	v_cndmask_b32_e32 v77, v77, v201, vcc
	v_lshlrev_b32_e32 v77, 2, v77
	v_cmp_gt_u32_e32 vcc, 2, v68
	s_waitcnt lgkmcnt(0)
	s_nop 1
	v_add_f32_dpp v76, v76, v76 row_shr:2 row_mask:0xf bank_mask:0xf
	v_add_u32_e32 v77, -4, v201
	v_cmp_lt_i32_e32 vcc, v77, v202
	s_nop 1
	v_cndmask_b32_e32 v77, v77, v201, vcc
	v_lshlrev_b32_e32 v77, 2, v77
	v_cmp_gt_u32_e32 vcc, 4, v68
	s_waitcnt lgkmcnt(0)
	s_nop 1
	v_add_f32_dpp v76, v76, v76 row_shr:4 row_mask:0xf bank_mask:0xf
	v_add_u32_e32 v77, -8, v201
	v_cmp_lt_i32_e32 vcc, v77, v202
	s_nop 1
	v_cndmask_b32_e32 v77, v77, v201, vcc
	v_lshlrev_b32_e32 v77, 2, v77
	v_cmp_gt_u32_e32 vcc, 8, v68
	s_waitcnt lgkmcnt(0)
	s_nop 1
	v_add_f32_dpp v76, v76, v76 row_shr:8 row_mask:0xf bank_mask:0xf
	v_add_u32_e32 v77, -16, v201
	v_cmp_lt_i32_e32 vcc, v77, v202
	s_nop 1
	v_cndmask_b32_e32 v77, v77, v201, vcc
	v_lshlrev_b32_e32 v77, 2, v77
	v_cmp_gt_u32_e32 vcc, 16, v68
	s_waitcnt lgkmcnt(0)
	s_nop 1
	v_add_f32_dpp v76, v76, v76 row_bcast:15 row_mask:0xa bank_mask:0xf
	v_subrev_u32_e32 v77, 32, v201
	v_cmp_lt_i32_e32 vcc, v77, v202
	s_nop 1
	v_cndmask_b32_e32 v77, v77, v201, vcc
	v_lshlrev_b32_e32 v77, 2, v77
	v_cmp_gt_u32_e32 vcc, 32, v68
	s_waitcnt lgkmcnt(0)
	s_nop 1
	v_add_f32_dpp v76, v76, v76 row_bcast:31 row_mask:0xc bank_mask:0xf
	v_lshlrev_b32_e32 v77, 2, v68
	v_lshl_or_b32 v77, s39, 8, v77
	v_add_u32_e32 v77, 0, v77
	v_add_u32_e32 v78, 0x1a640, v77
	ds_write_b32 v78, v75
	v_mul_f32_e32 v75, 0x3fb8aa3b, v76
	v_add_u32_e32 v76, 0x1c640, v77
	ds_write_b32 v76, v75
	s_andn2_b64 vcc, exec, s[6:7]
	s_cbranch_vccz .LBB0_553

; __device__ __forceinline__ float bf2f(bf16_t h) { return __uint_as_float(((unsigned)h) << 16); }
; __device__ __forceinline__ void ssd_item(const Args& a, LAS unsigned char* lds, int layer, bool is_sample, int b, int h, int seq_row0, int nchunks,
;                                          bf16_t* proj, float* ssq, const int tid) {
;     ...
;                 const float x = bf2f(dr[q]) + dtb;
;                 const float dt = x > 20.f ? x : log1pf(__expf(x));
;                 float sc = dt * Aneg;
; #pragma unroll
;                 for (int off = 1; off < 64; off <<= 1) { const float v = __shfl_up(sc, off); if (lane >= off) sc += v; }
;                 dt_all[cc * 64 + lane] = dt; ac_all[cc * 64 + lane] = sc * 1.4426950408889634f; } }
.LBB0_551:
	s_or_b64 exec, exec, s[20:21]
	v_add_u32_e32 v78, -1, v201
	v_cmp_lt_i32_e32 vcc, v78, v202
	v_mul_f32_e64 v77, v76, -v72
	s_and_b32 s20, s15, 0x3fffffc0
	v_cndmask_b32_e32 v78, v78, v201, vcc
	v_lshlrev_b32_e32 v78, 2, v78
	v_cmp_eq_u32_e32 vcc, 0, v68
	s_waitcnt lgkmcnt(0)
	s_nop 1
	v_add_f32_dpp v77, v77, v77 row_shr:1 row_mask:0xf bank_mask:0xf
	v_add_u32_e32 v78, -2, v201
	v_cmp_lt_i32_e32 vcc, v78, v202
	s_nop 1
	v_cndmask_b32_e32 v78, v78, v201, vcc
	v_lshlrev_b32_e32 v78, 2, v78
	v_cmp_gt_u32_e32 vcc, 2, v68
	s_waitcnt lgkmcnt(0)
	s_nop 1
	v_add_f32_dpp v77, v77, v77 row_shr:2 row_mask:0xf bank_mask:0xf
	v_add_u32_e32 v78, -4, v201
	v_cmp_lt_i32_e32 vcc, v78, v202
	s_nop 1
	v_cndmask_b32_e32 v78, v78, v201, vcc
	v_lshlrev_b32_e32 v78, 2, v78
	v_cmp_gt_u32_e32 vcc, 4, v68
	s_waitcnt lgkmcnt(0)
	s_nop 1
	v_add_f32_dpp v77, v77, v77 row_shr:4 row_mask:0xf bank_mask:0xf
	v_add_u32_e32 v78, -8, v201
	v_cmp_lt_i32_e32 vcc, v78, v202
	s_nop 1
	v_cndmask_b32_e32 v78, v78, v201, vcc
	v_lshlrev_b32_e32 v78, 2, v78
	v_cmp_gt_u32_e32 vcc, 8, v68
	s_waitcnt lgkmcnt(0)
	s_nop 1
	v_add_f32_dpp v77, v77, v77 row_shr:8 row_mask:0xf bank_mask:0xf
	v_add_u32_e32 v78, -16, v201
	v_cmp_lt_i32_e32 vcc, v78, v202
	s_nop 1
	v_cndmask_b32_e32 v78, v78, v201, vcc
	v_lshlrev_b32_e32 v78, 2, v78
	v_cmp_gt_u32_e32 vcc, 16, v68
	s_waitcnt lgkmcnt(0)
	s_nop 1
	v_add_f32_dpp v77, v77, v77 row_bcast:15 row_mask:0xa bank_mask:0xf
	v_subrev_u32_e32 v78, 32, v201
	v_cmp_lt_i32_e32 vcc, v78, v202
	s_nop 1
	v_cndmask_b32_e32 v78, v78, v201, vcc
	v_lshlrev_b32_e32 v78, 2, v78
	v_cmp_gt_u32_e32 vcc, 32, v68
	s_waitcnt lgkmcnt(0)
	s_nop 1
	v_add_f32_dpp v77, v77, v77 row_bcast:31 row_mask:0xc bank_mask:0xf
	v_or_b32_e32 v78, s20, v68
	v_lshl_add_u32 v78, v78, 2, 0
	v_add_u32_e32 v79, 0x1a640, v78
	ds_write_b32 v79, v76
	v_mul_f32_e32 v76, 0x3fb8aa3b, v77
	v_add_u32_e32 v77, 0x1c640, v78
	ds_write_b32 v77, v76
	s_andn2_b64 vcc, exec, s[16:17]
	s_cbranch_vccz .LBB0_544

; __device__ __forceinline__ float bf2f(bf16_t h) { return __uint_as_float(((unsigned)h) << 16); }
; __device__ __forceinline__ void ssd_item(const Args& a, LAS unsigned char* lds, int layer, bool is_sample, int b, int h, int seq_row0, int nchunks,
;                                          bf16_t* proj, float* ssq, const int tid) {
;     ...
;                 const float x = bf2f(dr[q]) + dtb;
;                 const float dt = x > 20.f ? x : log1pf(__expf(x));
;                 float sc = dt * Aneg;
; #pragma unroll
;                 for (int off = 1; off < 64; off <<= 1) { const float v = __shfl_up(sc, off); if (lane >= off) sc += v; }
;                 dt_all[cc * 64 + lane] = dt; ac_all[cc * 64 + lane] = sc * 1.4426950408889634f; } }
.LBB0_555:
	s_or_b64 exec, exec, s[6:7]
	v_add_u32_e32 v76, -1, v201
	v_cmp_lt_i32_e32 vcc, v76, v202
	v_mul_f32_e64 v75, v74, -v72
	s_nop 0
	v_cndmask_b32_e32 v76, v76, v201, vcc
	v_lshlrev_b32_e32 v76, 2, v76
	v_cmp_eq_u32_e32 vcc, 0, v68
	s_waitcnt lgkmcnt(0)
	s_nop 1
	v_add_f32_dpp v75, v75, v75 row_shr:1 row_mask:0xf bank_mask:0xf
	v_add_u32_e32 v76, -2, v201
	v_cmp_lt_i32_e32 vcc, v76, v202
	s_nop 1
	v_cndmask_b32_e32 v76, v76, v201, vcc
	v_lshlrev_b32_e32 v76, 2, v76
	v_cmp_gt_u32_e32 vcc, 2, v68
	s_waitcnt lgkmcnt(0)
	s_nop 1
	v_add_f32_dpp v75, v75, v75 row_shr:2 row_mask:0xf bank_mask:0xf
	v_add_u32_e32 v76, -4, v201
	v_cmp_lt_i32_e32 vcc, v76, v202
	s_nop 1
	v_cndmask_b32_e32 v76, v76, v201, vcc
	v_lshlrev_b32_e32 v76, 2, v76
	v_cmp_gt_u32_e32 vcc, 4, v68
	s_waitcnt lgkmcnt(0)
	s_nop 1
	v_add_f32_dpp v75, v75, v75 row_shr:4 row_mask:0xf bank_mask:0xf
	v_add_u32_e32 v76, -8, v201
	v_cmp_lt_i32_e32 vcc, v76, v202
	s_nop 1
	v_cndmask_b32_e32 v76, v76, v201, vcc
	v_lshlrev_b32_e32 v76, 2, v76
	v_cmp_gt_u32_e32 vcc, 8, v68
	s_waitcnt lgkmcnt(0)
	s_nop 1
	v_add_f32_dpp v75, v75, v75 row_shr:8 row_mask:0xf bank_mask:0xf
	v_add_u32_e32 v76, -16, v201
	v_cmp_lt_i32_e32 vcc, v76, v202
	s_nop 1
	v_cndmask_b32_e32 v76, v76, v201, vcc
	v_lshlrev_b32_e32 v76, 2, v76
	v_cmp_gt_u32_e32 vcc, 16, v68
	s_waitcnt lgkmcnt(0)
	s_nop 1
	v_add_f32_dpp v75, v75, v75 row_bcast:15 row_mask:0xa bank_mask:0xf
	v_subrev_u32_e32 v76, 32, v201
	v_cmp_lt_i32_e32 vcc, v76, v202
	s_nop 1
	v_cndmask_b32_e32 v76, v76, v201, vcc
	v_lshlrev_b32_e32 v76, 2, v76
	v_cmp_gt_u32_e32 vcc, 32, v68
	s_waitcnt lgkmcnt(0)
	s_nop 1
	v_add_f32_dpp v75, v75, v75 row_bcast:31 row_mask:0xc bank_mask:0xf
	v_lshlrev_b32_e32 v76, 2, v68
	v_lshl_or_b32 v76, s38, 8, v76
	v_add_u32_e32 v76, 0, v76
	v_add_u32_e32 v77, 0x1a640, v76
	ds_write_b32 v77, v74
	v_mul_f32_e32 v74, 0x3fb8aa3b, v75
	v_add_u32_e32 v75, 0x1c640, v76
	ds_write_b32 v75, v74
	s_andn2_b64 vcc, exec, s[4:5]
	s_cbranch_vccnz .LBB0_559

; __device__ __forceinline__ float bf2f(bf16_t h) { return __uint_as_float(((unsigned)h) << 16); }
; __device__ __forceinline__ void ssd_item(const Args& a, LAS unsigned char* lds, int layer, bool is_sample, int b, int h, int seq_row0, int nchunks,
;                                          bf16_t* proj, float* ssq, const int tid) {
;     ...
;                 const float x = bf2f(dr[q]) + dtb;
;                 const float dt = x > 20.f ? x : log1pf(__expf(x));
;                 float sc = dt * Aneg;
; #pragma unroll
;                 for (int off = 1; off < 64; off <<= 1) { const float v = __shfl_up(sc, off); if (lane >= off) sc += v; }
;                 dt_all[cc * 64 + lane] = dt; ac_all[cc * 64 + lane] = sc * 1.4426950408889634f; } }
.LBB0_558:
	s_or_b64 exec, exec, s[4:5]
	v_add_u32_e32 v74, -1, v201
	v_cmp_lt_i32_e32 vcc, v74, v202
	v_mul_f32_e64 v73, v71, -v72
	s_nop 0
	v_cndmask_b32_e32 v74, v74, v201, vcc
	v_lshlrev_b32_e32 v74, 2, v74
	v_cmp_eq_u32_e32 vcc, 0, v68
	s_waitcnt lgkmcnt(0)
	v_mov_b32_e32 v72, v73
	s_nop 1
	v_add_f32_dpp v72, v72, v72 row_shr:1 row_mask:0xf bank_mask:0xf
	v_add_u32_e32 v73, -2, v201
	v_cmp_lt_i32_e32 vcc, v73, v202
	s_nop 1
	v_cndmask_b32_e32 v73, v73, v201, vcc
	v_lshlrev_b32_e32 v73, 2, v73
	v_cmp_gt_u32_e32 vcc, 2, v68
	s_waitcnt lgkmcnt(0)
	s_nop 1
	v_add_f32_dpp v72, v72, v72 row_shr:2 row_mask:0xf bank_mask:0xf
	v_add_u32_e32 v73, -4, v201
	v_cmp_lt_i32_e32 vcc, v73, v202
	s_nop 1
	v_cndmask_b32_e32 v73, v73, v201, vcc
	v_lshlrev_b32_e32 v73, 2, v73
	v_cmp_gt_u32_e32 vcc, 4, v68
	s_waitcnt lgkmcnt(0)
	s_nop 1
	v_add_f32_dpp v72, v72, v72 row_shr:4 row_mask:0xf bank_mask:0xf
	v_add_u32_e32 v73, -8, v201
	v_cmp_lt_i32_e32 vcc, v73, v202
	s_nop 1
	v_cndmask_b32_e32 v73, v73, v201, vcc
	v_lshlrev_b32_e32 v73, 2, v73
	v_cmp_gt_u32_e32 vcc, 8, v68
	s_waitcnt lgkmcnt(0)
	s_nop 1
	v_add_f32_dpp v72, v72, v72 row_shr:8 row_mask:0xf bank_mask:0xf
	v_add_u32_e32 v73, -16, v201
	v_cmp_lt_i32_e32 vcc, v73, v202
	s_nop 1
	v_cndmask_b32_e32 v73, v73, v201, vcc
	v_lshlrev_b32_e32 v73, 2, v73
	v_cmp_gt_u32_e32 vcc, 16, v68
	s_waitcnt lgkmcnt(0)
	s_nop 1
	v_add_f32_dpp v72, v72, v72 row_bcast:15 row_mask:0xa bank_mask:0xf
	v_subrev_u32_e32 v73, 32, v201
	v_cmp_lt_i32_e32 vcc, v73, v202
	s_nop 1
	v_cndmask_b32_e32 v73, v73, v201, vcc
	v_lshlrev_b32_e32 v73, 2, v73
	v_cmp_gt_u32_e32 vcc, 32, v68
	s_waitcnt lgkmcnt(0)
	s_nop 1
	v_add_f32_dpp v72, v72, v72 row_bcast:31 row_mask:0xc bank_mask:0xf
	v_lshlrev_b32_e32 v73, 2, v68
	v_lshl_or_b32 v73, s22, 8, v73
	v_add_u32_e32 v73, 0, v73
	v_add_u32_e32 v74, 0x1a640, v73
	ds_write_b32 v74, v71
	v_mul_f32_e32 v71, 0x3fb8aa3b, v72
	v_add_u32_e32 v72, 0x1c640, v73
	ds_write_b32 v72, v71
